# P1: the convert-first half is chosen by XCD parity (blockIdx bit 0) instead of bit 3, so each XCD's GEMM workgroups stay in step and keep sharing tiles in L2
# baseline (speedup 1.0000x reference)
.LBB0_264:
	s_cmp_lt_i32 s86, 2
	s_cselect_b64 s[0:1], -1, 0
	s_cmp_gt_i32 s87, 1
	s_cselect_b64 s[2:3], -1, 0
	s_and_b64 s[0:1], s[0:1], s[2:3]
	s_andn2_b64 vcc, exec, s[0:1]
	s_cbranch_vccnz .LBB0_335
	s_mov_b32 s94, 2
	s_bitcmp1_b32 s33, 0
	s_cbranch_scc0 .Lmy_p1_pre
	s_mov_b32 s94, 0
